# GEMM unit start: accumulator clears done with 64-bit moves (half the instructions)
# baseline (speedup 1.0000x reference)
;     __device__ __forceinline__ bool next(int i, Unit& u) const { Unit t; if (!pg8::StaticOrder::next(i / 3, t)) return false; const int k = i % 3; u.pm = t.pm + k * NPANEL; u.pn = t.pn + 4 * k; return true; }
;     __device__ __forceinline__ bool next(int i, Unit& u) const { if (i > 0 || c >= 8) return false; u.pm = 256 + (c >> 2); u.pn = c & 3; return true; }
;     __device__ __forceinline__ bool next(int i, Unit& u) const { if (i > 0 || c >= 16) return false; u.pm = 256 + ((c >> 2) & 1); u.pn = c & 3; return true; }
;     __device__ __forceinline__ bool next(int i, Unit& u) const { if (i > 2) return false; u.pm = 256 + (c >> 2) + i * NPANEL; u.pn = (c & 3) + 4 * i; return true; }
;     __device__ __forceinline__ bool next(int i, Unit& u) const { if (i > 0) return false; const int p = c >= 22 ? 1 : 0; u.pm = 256 + p; u.pn = c - 22 * p; return true; }
; template <class Epi, class Sched, bool ALIGN_EPI = false, bool SP2 = false>
; __device__ __forceinline__ void gemm_phase(PG8_LAS unsigned char* lds, const Gemm g, const Sched& S, const Epi& E, const int wave_id) {
;     ...
;     f32x4 acc[2][2][4][2];
; #pragma unroll
;     for (int a = 0; a < 2; ++a)
; #pragma unroll
;         for (int b = 0; b < 2; ++b)
; #pragma unroll
;             for (int m = 0; m < 4; ++m)
; #pragma unroll
;                 for (int n = 0; n < 2; ++n) acc[a][b][m][n] = (f32x4){0.f, 0.f, 0.f, 0.f};
;     ...
;         const bool has_next = S.next(ui + 1, nxt);
;         const char* nA = has_next ? (const char*)g.A + (size_t)nxt.pm * tstep : cA; const char* nB = has_next ? (const char*)g.Bt + (size_t)nxt.pn * tstep : cB;
;         for (int t = 0; t < nt; t += 2) {
;             const bool last = (t == nt - 2);
;             const char* a1 = cA + (size_t)(t + 1) * kstep;
;             const char* a2 = last ? nA : cA + (size_t)(t + 2) * kstep; const char* b2 = last ? nB : cB + (size_t)(t + 2) * kstep;
.LBB0_156:
	s_ashr_i32 s13, s12, 31
	s_lshl_b64 s[14:15], s[12:13], 19
	s_add_u32 s14, s35, s14
	s_addc_u32 s15, s36, s15
	s_and_b64 s[16:17], s[4:5], exec
	s_cselect_b32 s13, s15, s21
	s_cselect_b32 s68, s14, s20
	s_ashr_i32 s11, s10, 31
	s_lshl_b64 s[16:17], s[10:11], 19
	s_add_u32 s16, s37, s16
	s_addc_u32 s17, s38, s17
	s_and_b64 s[26:27], s[4:5], exec
	s_cselect_b32 s11, s17, s23
	s_cselect_b32 s69, s16, s22
	s_cmp_eq_u32 s24, 0
	s_cselect_b64 s[24:25], -1, 0
	s_add_u32 s74, s22, 0x100
	s_addc_u32 s75, s23, 0
	s_add_u32 s22, s20, 0x40080
	s_addc_u32 s23, s21, 0
	v_mov_b32_e32 v2, 0
	v_mov_b64_e32 v[196:197], 0x400
	v_cndmask_b32_e64 v250, 0, 1, s[24:25]
	v_lshl_add_u64 v[222:223], s[22:23], 0, v[218:219]
	v_lshl_add_u64 v[224:225], s[22:23], 0, v[220:221]
	s_mov_b32 s76, -2
	s_mov_b64 s[22:23], 0
	v_mov_b32_e32 v3, v2
	v_mov_b64_e32 v[4:5], 0
	v_mov_b64_e32 v[6:7], 0
	v_mov_b64_e32 v[8:9], 0
	v_mov_b64_e32 v[10:11], 0
	v_mov_b64_e32 v[12:13], 0
	v_mov_b64_e32 v[14:15], 0
	v_mov_b64_e32 v[16:17], 0
	v_mov_b64_e32 v[18:19], 0
	v_mov_b64_e32 v[20:21], 0
	v_mov_b64_e32 v[22:23], 0
	v_mov_b64_e32 v[24:25], 0
	v_mov_b64_e32 v[26:27], 0
	v_mov_b64_e32 v[28:29], 0
	v_mov_b64_e32 v[30:31], 0
	v_mov_b64_e32 v[32:33], 0
	v_mov_b64_e32 v[34:35], 0
	v_mov_b64_e32 v[36:37], 0
	v_mov_b64_e32 v[38:39], 0
	v_mov_b64_e32 v[40:41], 0
	v_mov_b64_e32 v[42:43], 0
	v_mov_b64_e32 v[44:45], 0
	v_mov_b64_e32 v[46:47], 0
	v_mov_b64_e32 v[48:49], 0
	v_mov_b64_e32 v[50:51], 0
	v_mov_b64_e32 v[52:53], 0
	v_mov_b64_e32 v[54:55], 0
	v_mov_b64_e32 v[56:57], 0
	v_mov_b64_e32 v[58:59], 0
	v_mov_b64_e32 v[60:61], 0
	v_mov_b64_e32 v[62:63], 0
	v_mov_b64_e32 v[64:65], 0
	v_mov_b64_e32 v[66:67], 0
	v_mov_b64_e32 v[68:69], 0
	v_mov_b64_e32 v[70:71], 0
	v_mov_b64_e32 v[72:73], 0
	v_mov_b64_e32 v[74:75], 0
	v_mov_b64_e32 v[76:77], 0
	v_mov_b64_e32 v[78:79], 0
	v_mov_b64_e32 v[80:81], 0
	v_mov_b64_e32 v[82:83], 0
	v_mov_b64_e32 v[84:85], 0
	v_mov_b64_e32 v[86:87], 0
	v_mov_b64_e32 v[88:89], 0
	v_mov_b64_e32 v[90:91], 0
	v_mov_b64_e32 v[92:93], 0
	v_mov_b64_e32 v[94:95], 0
	v_mov_b64_e32 v[96:97], 0
	v_mov_b64_e32 v[98:99], 0
	v_mov_b64_e32 v[100:101], 0
	v_mov_b64_e32 v[102:103], 0
	v_mov_b64_e32 v[104:105], 0
	v_mov_b64_e32 v[106:107], 0
	v_mov_b64_e32 v[108:109], 0
	v_mov_b64_e32 v[110:111], 0
	v_mov_b64_e32 v[112:113], 0
	v_mov_b64_e32 v[114:115], 0
	v_mov_b64_e32 v[116:117], 0
	v_mov_b64_e32 v[118:119], 0
	v_mov_b64_e32 v[120:121], 0
	v_mov_b64_e32 v[122:123], 0
	v_mov_b64_e32 v[124:125], 0
	v_mov_b64_e32 v[126:127], 0
	v_mov_b64_e32 v[128:129], 0
	s_branch .LBB0_158

;     __device__ __forceinline__ bool next(int i, Unit& u) const { Unit t; if (!pg8::StaticOrder::next(i / 3, t)) return false; const int k = i % 3; u.pm = t.pm + k * NPANEL; u.pn = t.pn + 4 * k; return true; }
;     __device__ __forceinline__ bool next(int i, Unit& u) const { if (i > 0 || c >= 8) return false; u.pm = 256 + (c >> 2); u.pn = c & 3; return true; }
;     __device__ __forceinline__ bool next(int i, Unit& u) const { if (i > 0 || c >= 16) return false; u.pm = 256 + ((c >> 2) & 1); u.pn = c & 3; return true; }
;     __device__ __forceinline__ bool next(int i, Unit& u) const { if (i > 2) return false; u.pm = 256 + (c >> 2) + i * NPANEL; u.pn = (c & 3) + 4 * i; return true; }
;     __device__ __forceinline__ bool next(int i, Unit& u) const { if (i > 0) return false; const int p = c >= 22 ? 1 : 0; u.pm = 256 + p; u.pn = c - 22 * p; return true; }
; template <class Epi, class Sched, bool ALIGN_EPI = false, bool SP2 = false>
; __device__ __forceinline__ void gemm_phase(PG8_LAS unsigned char* lds, const Gemm g, const Sched& S, const Epi& E, const int wave_id) {
;     ...
;     f32x4 acc[2][2][4][2];
; #pragma unroll
;     for (int a = 0; a < 2; ++a)
; #pragma unroll
;         for (int b = 0; b < 2; ++b)
; #pragma unroll
;             for (int m = 0; m < 4; ++m)
; #pragma unroll
;                 for (int n = 0; n < 2; ++n) acc[a][b][m][n] = (f32x4){0.f, 0.f, 0.f, 0.f};
;     ...
;         const bool has_next = S.next(ui + 1, nxt);
;         const char* nA = has_next ? (const char*)g.A + (size_t)nxt.pm * tstep : cA; const char* nB = has_next ? (const char*)g.Bt + (size_t)nxt.pn * tstep : cB;
;         for (int t = 0; t < nt; t += 2) {
;             const bool last = (t == nt - 2);
;             const char* a1 = cA + (size_t)(t + 1) * kstep;
;             const char* a2 = last ? nA : cA + (size_t)(t + 2) * kstep; const char* b2 = last ? nB : cB + (size_t)(t + 2) * kstep;
.LBB0_234:
	s_cmp_eq_u32 s16, 0
	s_cselect_b64 s[16:17], -1, 0
	s_add_u32 s57, s14, 0x100
	s_addc_u32 s62, s15, 0
	s_add_u32 s14, s12, 0xb0080
	s_addc_u32 s15, s13, 0
	v_mov_b32_e32 v2, 0
	v_cndmask_b32_e64 v248, 0, 1, s[16:17]
	v_lshl_add_u64 v[222:223], s[14:15], 0, v[218:219]
	v_lshl_add_u64 v[224:225], s[14:15], 0, v[220:221]
	s_mov_b32 s63, -2
	s_mov_b64 s[14:15], 0
	v_mov_b32_e32 v3, v2
	v_mov_b64_e32 v[4:5], 0
	v_mov_b64_e32 v[6:7], 0
	v_mov_b64_e32 v[8:9], 0
	v_mov_b64_e32 v[10:11], 0
	v_mov_b64_e32 v[12:13], 0
	v_mov_b64_e32 v[14:15], 0
	v_mov_b64_e32 v[16:17], 0
	v_mov_b64_e32 v[18:19], 0
	v_mov_b64_e32 v[20:21], 0
	v_mov_b64_e32 v[22:23], 0
	v_mov_b64_e32 v[24:25], 0
	v_mov_b64_e32 v[26:27], 0
	v_mov_b64_e32 v[28:29], 0
	v_mov_b64_e32 v[30:31], 0
	v_mov_b64_e32 v[32:33], 0
	v_mov_b64_e32 v[34:35], 0
	v_mov_b64_e32 v[36:37], 0
	v_mov_b64_e32 v[38:39], 0
	v_mov_b64_e32 v[40:41], 0
	v_mov_b64_e32 v[42:43], 0
	v_mov_b64_e32 v[44:45], 0
	v_mov_b64_e32 v[46:47], 0
	v_mov_b64_e32 v[48:49], 0
	v_mov_b64_e32 v[50:51], 0
	v_mov_b64_e32 v[52:53], 0
	v_mov_b64_e32 v[54:55], 0
	v_mov_b64_e32 v[56:57], 0
	v_mov_b64_e32 v[58:59], 0
	v_mov_b64_e32 v[60:61], 0
	v_mov_b64_e32 v[62:63], 0
	v_mov_b64_e32 v[64:65], 0
	v_mov_b64_e32 v[66:67], 0
	v_mov_b64_e32 v[68:69], 0
	v_mov_b64_e32 v[70:71], 0
	v_mov_b64_e32 v[72:73], 0
	v_mov_b64_e32 v[74:75], 0
	v_mov_b64_e32 v[76:77], 0
	v_mov_b64_e32 v[78:79], 0
	v_mov_b64_e32 v[80:81], 0
	v_mov_b64_e32 v[82:83], 0
	v_mov_b64_e32 v[84:85], 0
	v_mov_b64_e32 v[86:87], 0
	v_mov_b64_e32 v[88:89], 0
	v_mov_b64_e32 v[90:91], 0
	v_mov_b64_e32 v[92:93], 0
	v_mov_b64_e32 v[94:95], 0
	v_mov_b64_e32 v[96:97], 0
	v_mov_b64_e32 v[98:99], 0
	v_mov_b64_e32 v[100:101], 0
	v_mov_b64_e32 v[102:103], 0
	v_mov_b64_e32 v[104:105], 0
	v_mov_b64_e32 v[106:107], 0
	v_mov_b64_e32 v[108:109], 0
	v_mov_b64_e32 v[110:111], 0
	v_mov_b64_e32 v[112:113], 0
	v_mov_b64_e32 v[114:115], 0
	v_mov_b64_e32 v[116:117], 0
	v_mov_b64_e32 v[118:119], 0
	v_mov_b64_e32 v[120:121], 0
	v_mov_b64_e32 v[122:123], 0
	v_mov_b64_e32 v[124:125], 0
	v_mov_b64_e32 v[126:127], 0
	v_mov_b64_e32 v[128:129], 0
	s_branch .LBB0_236

; #define PG8_STAGE(bufoff, gbase, voff) do { _Pragma("unroll") for (int _i = 0; _i < 2; ++_i) \
;         __builtin_amdgcn_global_load_lds((const unsigned*)((const char*)(gbase) + (voff)[_i]), (PG8_LAS unsigned*)(lds + (bufoff) + ldsw + _i * 8192), 16, 0, 0); } while (0)
; #define PG8_WAIT_V(n) asm volatile("s_waitcnt vmcnt(" #n ")" ::: "memory")
; #define PG8_BAR __builtin_amdgcn_s_barrier()
; template <class Epi, class Sched, bool ALIGN_EPI = false, bool SP2 = false>
; __device__ __forceinline__ void gemm_phase(PG8_LAS unsigned char* lds, const Gemm g, const Sched& S, const Epi& E, const int wave_id) {
;     ...
;     for (int i = 0; i < 2; ++i) { int R, C; stage_rc(tid * 16 + i * 8192, R, C); const int Rb = Epi::PERM ? ((R & ~31) + perm32(R & 31)) : R;
;         voffA[i] = (unsigned)(R * LD + C) * 2u; voffB[i] = (unsigned)(Rb * LD + C) * 2u; }
;     ...
;     f32x4 acc[2][2][4][2];
; #pragma unroll
;     for (int a = 0; a < 2; ++a)
; #pragma unroll
;         for (int b = 0; b < 2; ++b)
; #pragma unroll
;             for (int m = 0; m < 4; ++m)
; #pragma unroll
;                 for (int n = 0; n < 2; ++n) acc[a][b][m][n] = (f32x4){0.f, 0.f, 0.f, 0.f};
;     bf16x8 At[4][2], B0[2][2], B1[2][2];
;     const char* cA = (const char*)g.A + (size_t)cur.pm * tstep; const char* cB = (const char*)g.Bt + (size_t)cur.pn * tstep;
;     S.a_ready(cur);
;     if constexpr (SP2) {
;         PG8_STAGE(PG8_SB(0, 0), cB, voffB); PG8_STAGE(PG8_SB(0, 1), cB + hstep, voffB); PG8_STAGE(PG8_SA(0, 0), cA, voffA); PG8_STAGE(PG8_SA(0, 1), cA + hstep, voffA);
;         if (wr == 1) PG8_BAR;
;         PG8_WAIT_V(2); PG8_BAR;
;         PG8_STAGE(PG8_SB(1, 0), cB + kstep, voffB); PG8_STAGE(PG8_SA(1, 0), cA + kstep, voffA); PG8_STAGE(PG8_SB(1, 1), cB + hstep + kstep, voffB);
;         PG8_WAIT_V(6); PG8_BAR;
.LBB0_303:
	v_and_b32_e32 v230, 15, v13
	v_bfe_u32 v1, v13, 4, 2
	v_lshlrev_b32_e32 v19, 6, v230
	v_lshlrev_b32_e32 v13, 2, v13
	s_and_b32 s27, s5, 3
	v_lshl_or_b32 v19, v1, 4, v19
	s_lshl_b32 s31, s19, 13
	v_and_b32_e32 v13, 32, v13
	v_bitop3_b32 v20, v19, s31, v13 bitop3:0xde
	s_lshl_b32 s31, s27, 12
	s_add_i32 m0, s22, 0x18000
	v_lshl_add_u64 v[8:9], v[8:9], 0, s[64:65]
	v_bitop3_b32 v231, v19, s31, v13 bitop3:0xde
	s_waitcnt vmcnt(2)
	s_barrier
	global_load_lds_dwordx4 v[8:9], off
	v_lshl_add_u64 v[6:7], v[6:7], 0, s[64:65]
	s_add_i32 m0, s22, 0x1a000
	s_add_i32 s31, s22, 0x8000
	s_add_i32 s34, s22, 0xa000
	global_load_lds_dwordx4 v[6:7], off
	v_lshl_add_u64 v[4:5], v[4:5], 0, s[64:65]
	s_mov_b32 m0, s31
	s_add_u32 s36, s6, 0xb0080
	global_load_lds_dwordx4 v[4:5], off
	v_lshl_add_u64 v[2:3], v[2:3], 0, s[64:65]
	s_mov_b32 m0, s34
	s_addc_u32 s37, s7, 0
	global_load_lds_dwordx4 v[2:3], off
	s_add_i32 m0, s22, 0x1c000
	v_lshl_add_u64 v[2:3], s[36:37], 0, v[214:215]
	global_load_lds_dwordx4 v[2:3], off
	v_lshl_add_u64 v[2:3], s[36:37], 0, v[210:211]
	s_add_i32 m0, s22, 0x1e000
	v_readlane_b32 s35, v254, 56
	global_load_lds_dwordx4 v[2:3], off
	s_mul_i32 s35, s35, 0x3d00000
	s_add_u32 s17, s35, s17
	s_addc_u32 s35, 0, 0
	s_add_u32 s17, s17, s14
	s_addc_u32 s35, s35, s15
	s_add_u32 s12, s12, s17
	s_addc_u32 s13, s13, s35
	s_add_u32 s35, s12, 0x97ec0100
	s_addc_u32 s36, s13, 0
	s_mul_i32 s16, s16, 0x160000
	s_add_u32 s14, s16, s14
	s_addc_u32 s15, 0, s15
	s_movk_i32 s16, 0xb00
	v_lshrrev_b32_e32 v3, 1, v10
	v_mul_lo_u32 v2, v11, s16
	s_mov_b32 s17, 0xb000
	s_add_u32 s37, s10, s14
	v_mad_u64_u32 v[2:3], s[12:13], v3, s17, v[2:3]
	s_addc_u32 s38, s11, s15
	v_or_b32_e32 v2, v2, v12
	s_add_u32 s10, s37, 0x263b0080
	v_add_lshl_u32 v2, v2, v15, 1
	v_mov_b32_e32 v3, v0
	s_addc_u32 s11, s38, 0
	v_lshl_add_u64 v[218:219], s[10:11], 0, v[2:3]
	v_lshrrev_b32_e32 v3, 1, v14
	v_mul_lo_u32 v2, v16, s16
	v_mad_u64_u32 v[2:3], s[12:13], v3, s17, v[2:3]
	v_or_b32_e32 v2, v2, v17
	s_waitcnt vmcnt(6)
	v_add_lshl_u32 v2, v2, v18, 1
	v_mov_b32_e32 v3, v0
	v_lshl_add_u64 v[220:221], s[10:11], 0, v[2:3]
	v_mov_b32_e32 v2, 0
	s_mov_b32 s39, -2
	s_mov_b64 s[10:11], 0
	v_add_u32_e32 v232, 0, v20
	v_mov_b32_e32 v3, v2
	v_mov_b64_e32 v[4:5], 0
	v_mov_b64_e32 v[6:7], 0
	v_mov_b64_e32 v[8:9], 0
	v_mov_b64_e32 v[10:11], 0
	v_mov_b64_e32 v[12:13], 0
	v_mov_b64_e32 v[14:15], 0
	v_mov_b64_e32 v[16:17], 0
	v_mov_b64_e32 v[18:19], 0
	v_mov_b64_e32 v[20:21], 0
	v_mov_b64_e32 v[22:23], 0
	v_mov_b64_e32 v[24:25], 0
	v_mov_b64_e32 v[26:27], 0
	v_mov_b64_e32 v[28:29], 0
	v_mov_b64_e32 v[30:31], 0
	v_mov_b64_e32 v[32:33], 0
	v_mov_b64_e32 v[34:35], 0
	v_mov_b64_e32 v[36:37], 0
	v_mov_b64_e32 v[38:39], 0
	v_mov_b64_e32 v[40:41], 0
	v_mov_b64_e32 v[42:43], 0
	v_mov_b64_e32 v[44:45], 0
	v_mov_b64_e32 v[46:47], 0
	v_mov_b64_e32 v[48:49], 0
	v_mov_b64_e32 v[50:51], 0
	v_mov_b64_e32 v[52:53], 0
	v_mov_b64_e32 v[54:55], 0
	v_mov_b64_e32 v[56:57], 0
	v_mov_b64_e32 v[58:59], 0
	v_mov_b64_e32 v[60:61], 0
	v_mov_b64_e32 v[62:63], 0
	v_mov_b64_e32 v[64:65], 0
	v_mov_b64_e32 v[66:67], 0
	v_mov_b64_e32 v[68:69], 0
	v_mov_b64_e32 v[70:71], 0
	v_mov_b64_e32 v[72:73], 0
	v_mov_b64_e32 v[74:75], 0
	v_mov_b64_e32 v[76:77], 0
	v_mov_b64_e32 v[78:79], 0
	v_mov_b64_e32 v[80:81], 0
	v_mov_b64_e32 v[82:83], 0
	v_mov_b64_e32 v[84:85], 0
	v_mov_b64_e32 v[86:87], 0
	v_mov_b64_e32 v[88:89], 0
	v_mov_b64_e32 v[90:91], 0
	v_mov_b64_e32 v[92:93], 0
	v_mov_b64_e32 v[94:95], 0
	v_mov_b64_e32 v[96:97], 0
	v_mov_b64_e32 v[98:99], 0
	v_mov_b64_e32 v[100:101], 0
	v_mov_b64_e32 v[102:103], 0
	v_mov_b64_e32 v[104:105], 0
	v_mov_b64_e32 v[106:107], 0
	v_mov_b64_e32 v[108:109], 0
	v_mov_b64_e32 v[110:111], 0
	v_mov_b64_e32 v[112:113], 0
	v_mov_b64_e32 v[114:115], 0
	v_mov_b64_e32 v[116:117], 0
	v_mov_b64_e32 v[118:119], 0
	v_mov_b64_e32 v[120:121], 0
	v_mov_b64_e32 v[122:123], 0
	v_mov_b64_e32 v[124:125], 0
	v_mov_b64_e32 v[126:127], 0
	v_mov_b64_e32 v[128:129], 0
	s_barrier
	s_branch .LBB0_305

;     __device__ __forceinline__ bool next(int i, Unit& u) const { Unit t; if (!pg8::StaticOrder::next(i / 3, t)) return false; const int k = i % 3; u.pm = t.pm + k * NPANEL; u.pn = t.pn + 4 * k; return true; }
;     __device__ __forceinline__ bool next(int i, Unit& u) const { if (i > 0 || c >= 8) return false; u.pm = 256 + (c >> 2); u.pn = c & 3; return true; }
;     __device__ __forceinline__ bool next(int i, Unit& u) const { if (i > 0 || c >= 16) return false; u.pm = 256 + ((c >> 2) & 1); u.pn = c & 3; return true; }
;     __device__ __forceinline__ bool next(int i, Unit& u) const { if (i > 2) return false; u.pm = 256 + (c >> 2) + i * NPANEL; u.pn = (c & 3) + 4 * i; return true; }
;     __device__ __forceinline__ bool next(int i, Unit& u) const { if (i > 0) return false; const int p = c >= 22 ? 1 : 0; u.pm = 256 + p; u.pn = c - 22 * p; return true; }
; template <class Epi, class Sched, bool ALIGN_EPI = false, bool SP2 = false>
; __device__ __forceinline__ void gemm_phase(PG8_LAS unsigned char* lds, const Gemm g, const Sched& S, const Epi& E, const int wave_id) {
;     ...
;         const bool has_next = S.next(ui + 1, nxt);
;         const char* nA = has_next ? (const char*)g.A + (size_t)nxt.pm * tstep : cA; const char* nB = has_next ? (const char*)g.Bt + (size_t)nxt.pn * tstep : cB;
;         for (int t = 0; t < nt; t += 2) {
;             const bool last = (t == nt - 2);
;             const char* a1 = cA + (size_t)(t + 1) * kstep;
;             const char* a2 = last ? nA : cA + (size_t)(t + 2) * kstep; const char* b2 = last ? nB : cB + (size_t)(t + 2) * kstep;
;             const char* a3 = a2 + kstep; const char* b3 = b2 + kstep;
;             if (last && has_next) S.a_ready(nxt);
;             if constexpr (SP2) {
;             int tz_ = __builtin_amdgcn_readfirstlane(t | (ui > 0 ? 0 : 1)); asm volatile("" : "+s"(tz_));
;     ...
;         if (!keep_acc) {
; #pragma unroll
;         for (int a = 0; a < 2; ++a)
; #pragma unroll
;             for (int b = 0; b < 2; ++b)
; #pragma unroll
;                 for (int m = 0; m < 4; ++m)
; #pragma unroll
;                     for (int n = 0; n < 2; ++n) acc[a][b][m][n] = (f32x4){0.f, 0.f, 0.f, 0.f};
.LBB0_419:
	s_ashr_i32 s23, s22, 31
	s_lshl_b64 s[12:13], s[22:23], 19
	s_add_u32 s24, s54, s12
	s_addc_u32 s25, s55, s13
	s_and_b64 s[12:13], s[6:7], exec
	s_cselect_b32 s23, s25, s9
	s_cselect_b32 s29, s24, s8
	s_ashr_i32 s21, s20, 31
	s_lshl_b64 s[12:13], s[20:21], 19
	s_add_u32 s26, s67, s12
	s_addc_u32 s27, s74, s13
	s_and_b64 s[12:13], s[6:7], exec
	s_cselect_b32 s21, s27, s11
	s_cselect_b32 s31, s26, s10
	s_cmp_eq_u32 s14, 0
	s_cselect_b64 s[12:13], -1, 0
	s_add_u32 s36, s10, 0x100
	s_addc_u32 s37, s11, 0
	s_add_u32 s10, s8, 0x40080
	s_addc_u32 s11, s9, 0
	v_mov_b32_e32 v2, 0
	v_cndmask_b32_e64 v248, 0, 1, s[12:13]
	v_lshl_add_u64 v[222:223], s[10:11], 0, v[218:219]
	v_lshl_add_u64 v[224:225], s[10:11], 0, v[220:221]
	s_mov_b32 s40, -2
	s_mov_b64 s[10:11], 0
	v_mov_b32_e32 v3, v2
	v_mov_b64_e32 v[4:5], 0
	v_mov_b64_e32 v[6:7], 0
	v_mov_b64_e32 v[8:9], 0
	v_mov_b64_e32 v[10:11], 0
	v_mov_b64_e32 v[12:13], 0
	v_mov_b64_e32 v[14:15], 0
	v_mov_b64_e32 v[16:17], 0
	v_mov_b64_e32 v[18:19], 0
	v_mov_b64_e32 v[20:21], 0
	v_mov_b64_e32 v[22:23], 0
	v_mov_b64_e32 v[24:25], 0
	v_mov_b64_e32 v[26:27], 0
	v_mov_b64_e32 v[28:29], 0
	v_mov_b64_e32 v[30:31], 0
	v_mov_b64_e32 v[32:33], 0
	v_mov_b64_e32 v[34:35], 0
	v_mov_b64_e32 v[36:37], 0
	v_mov_b64_e32 v[38:39], 0
	v_mov_b64_e32 v[40:41], 0
	v_mov_b64_e32 v[42:43], 0
	v_mov_b64_e32 v[44:45], 0
	v_mov_b64_e32 v[46:47], 0
	v_mov_b64_e32 v[48:49], 0
	v_mov_b64_e32 v[50:51], 0
	v_mov_b64_e32 v[52:53], 0
	v_mov_b64_e32 v[54:55], 0
	v_mov_b64_e32 v[56:57], 0
	v_mov_b64_e32 v[58:59], 0
	v_mov_b64_e32 v[60:61], 0
	v_mov_b64_e32 v[62:63], 0
	v_mov_b64_e32 v[64:65], 0
	v_mov_b64_e32 v[66:67], 0
	v_mov_b64_e32 v[68:69], 0
	v_mov_b64_e32 v[70:71], 0
	v_mov_b64_e32 v[72:73], 0
	v_mov_b64_e32 v[74:75], 0
	v_mov_b64_e32 v[76:77], 0
	v_mov_b64_e32 v[78:79], 0
	v_mov_b64_e32 v[80:81], 0
	v_mov_b64_e32 v[82:83], 0
	v_mov_b64_e32 v[84:85], 0
	v_mov_b64_e32 v[86:87], 0
	v_mov_b64_e32 v[88:89], 0
	v_mov_b64_e32 v[90:91], 0
	v_mov_b64_e32 v[92:93], 0
	v_mov_b64_e32 v[94:95], 0
	v_mov_b64_e32 v[96:97], 0
	v_mov_b64_e32 v[98:99], 0
	v_mov_b64_e32 v[100:101], 0
	v_mov_b64_e32 v[102:103], 0
	v_mov_b64_e32 v[104:105], 0
	v_mov_b64_e32 v[106:107], 0
	v_mov_b64_e32 v[108:109], 0
	v_mov_b64_e32 v[110:111], 0
	v_mov_b64_e32 v[112:113], 0
	v_mov_b64_e32 v[114:115], 0
	v_mov_b64_e32 v[116:117], 0
	v_mov_b64_e32 v[118:119], 0
	v_mov_b64_e32 v[120:121], 0
	v_mov_b64_e32 v[122:123], 0
	v_mov_b64_e32 v[124:125], 0
	v_mov_b64_e32 v[126:127], 0
	v_mov_b64_e32 v[128:129], 0
	s_branch .LBB0_421

; #define PG8_STAGE(bufoff, gbase, voff) do { _Pragma("unroll") for (int _i = 0; _i < 2; ++_i) \
;         __builtin_amdgcn_global_load_lds((const unsigned*)((const char*)(gbase) + (voff)[_i]), (PG8_LAS unsigned*)(lds + (bufoff) + ldsw + _i * 8192), 16, 0, 0); } while (0)
; #define PG8_WAIT_V(n) asm volatile("s_waitcnt vmcnt(" #n ")" ::: "memory")
; #define PG8_BAR __builtin_amdgcn_s_barrier()
; template <class Epi, class Sched, bool ALIGN_EPI = false, bool SP2 = false>
; __device__ __forceinline__ void gemm_phase(PG8_LAS unsigned char* lds, const Gemm g, const Sched& S, const Epi& E, const int wave_id) {
;     ...
;     f32x4 acc[2][2][4][2];
; #pragma unroll
;     for (int a = 0; a < 2; ++a)
; #pragma unroll
;         for (int b = 0; b < 2; ++b)
; #pragma unroll
;             for (int m = 0; m < 4; ++m)
; #pragma unroll
;                 for (int n = 0; n < 2; ++n) acc[a][b][m][n] = (f32x4){0.f, 0.f, 0.f, 0.f};
;     bf16x8 At[4][2], B0[2][2], B1[2][2];
;     const char* cA = (const char*)g.A + (size_t)cur.pm * tstep; const char* cB = (const char*)g.Bt + (size_t)cur.pn * tstep;
;     S.a_ready(cur);
;     if constexpr (SP2) {
;         PG8_STAGE(PG8_SB(0, 0), cB, voffB); PG8_STAGE(PG8_SB(0, 1), cB + hstep, voffB); PG8_STAGE(PG8_SA(0, 0), cA, voffA); PG8_STAGE(PG8_SA(0, 1), cA + hstep, voffA);
;         if (wr == 1) PG8_BAR;
;         PG8_WAIT_V(2); PG8_BAR;
;         PG8_STAGE(PG8_SB(1, 0), cB + kstep, voffB); PG8_STAGE(PG8_SA(1, 0), cA + kstep, voffA); PG8_STAGE(PG8_SB(1, 1), cB + hstep + kstep, voffB);
;         PG8_WAIT_V(6); PG8_BAR;
.LBB0_1503:
	v_and_b32_e32 v230, 15, v1
	v_bfe_u32 v231, v1, 4, 2
	v_lshlrev_b32_e32 v16, 6, v230
	v_lshlrev_b32_e32 v1, 2, v1
	s_and_b32 s31, s23, 3
	v_lshl_or_b32 v16, v231, 4, v16
	s_lshl_b32 s21, s22, 13
	v_and_b32_e32 v1, 32, v1
	s_add_i32 m0, s25, 0x18000
	v_lshl_add_u64 v[8:9], v[8:9], 0, s[64:65]
	v_bitop3_b32 v17, v16, s21, v1 bitop3:0xde
	s_lshl_b32 s21, s31, 12
	s_waitcnt vmcnt(2)
	s_barrier
	global_load_lds_dwordx4 v[8:9], off
	v_lshl_add_u64 v[6:7], v[6:7], 0, s[64:65]
	s_add_i32 m0, s25, 0x1a000
	s_add_i32 s37, s25, 0x8000
	s_add_i32 s38, s25, 0xa000
	global_load_lds_dwordx4 v[6:7], off
	v_lshl_add_u64 v[4:5], v[4:5], 0, s[64:65]
	s_mov_b32 m0, s37
	s_add_u32 s40, s8, 0x40080
	global_load_lds_dwordx4 v[4:5], off
	v_lshl_add_u64 v[2:3], v[2:3], 0, s[64:65]
	s_mov_b32 m0, s38
	s_addc_u32 s41, s9, 0
	global_load_lds_dwordx4 v[2:3], off
	s_add_i32 m0, s25, 0x1c000
	v_lshl_add_u64 v[2:3], s[40:41], 0, v[214:215]
	global_load_lds_dwordx4 v[2:3], off
	v_lshl_add_u64 v[2:3], s[40:41], 0, v[210:211]
	s_add_i32 m0, s25, 0x1e000
	v_bitop3_b32 v1, v16, s21, v1 bitop3:0xde
	global_load_lds_dwordx4 v[2:3], off
	v_readlane_b32 s21, v254, 56
	s_mul_i32 s21, s21, 0x3d00000
	s_add_u32 s16, s16, s21
	s_addc_u32 s17, s17, 0
	s_add_u32 s16, s16, s20
	s_addc_u32 s17, s17, 0
	s_add_u32 s39, s16, 0x99e40100
	s_addc_u32 s40, s17, 0
	v_lshlrev_b32_e32 v2, 14, v10
	v_and_b32_e32 v2, 0xffff8000, v2
	s_add_u32 s41, s12, s18
	v_lshl_add_u32 v2, v11, 11, v2
	v_and_b32_e32 v3, 1, v10
	s_addc_u32 s42, s13, s19
	v_lshl_or_b32 v2, v3, 6, v2
	s_add_u32 s12, s41, 0x8f300080
	v_lshl_add_u32 v2, v13, 1, v2
	v_mov_b32_e32 v3, v0
	s_addc_u32 s13, s42, 0
	v_lshl_add_u64 v[218:219], s[12:13], 0, v[2:3]
	v_lshlrev_b32_e32 v2, 14, v12
	v_and_b32_e32 v2, 0xffff8000, v2
	v_lshl_add_u32 v2, v14, 11, v2
	v_and_b32_e32 v3, 1, v12
	v_lshl_or_b32 v2, v3, 6, v2
	s_waitcnt vmcnt(6)
	v_lshl_add_u32 v2, v15, 1, v2
	v_mov_b32_e32 v3, v0
	v_lshl_add_u64 v[220:221], s[12:13], 0, v[2:3]
	v_mov_b32_e32 v2, 0
	s_mov_b32 s43, -2
	s_mov_b64 s[12:13], 0
	v_add_u32_e32 v232, 0, v17
	v_mov_b32_e32 v3, v2
	v_mov_b64_e32 v[4:5], 0
	v_mov_b64_e32 v[6:7], 0
	v_mov_b64_e32 v[8:9], 0
	v_mov_b64_e32 v[10:11], 0
	v_mov_b64_e32 v[12:13], 0
	v_mov_b64_e32 v[14:15], 0
	v_mov_b64_e32 v[16:17], 0
	v_mov_b64_e32 v[18:19], 0
	v_mov_b64_e32 v[20:21], 0
	v_mov_b64_e32 v[22:23], 0
	v_mov_b64_e32 v[24:25], 0
	v_mov_b64_e32 v[26:27], 0
	v_mov_b64_e32 v[28:29], 0
	v_mov_b64_e32 v[30:31], 0
	v_mov_b64_e32 v[32:33], 0
	v_mov_b64_e32 v[34:35], 0
	v_mov_b64_e32 v[36:37], 0
	v_mov_b64_e32 v[38:39], 0
	v_mov_b64_e32 v[40:41], 0
	v_mov_b64_e32 v[42:43], 0
	v_mov_b64_e32 v[44:45], 0
	v_mov_b64_e32 v[46:47], 0
	v_mov_b64_e32 v[48:49], 0
	v_mov_b64_e32 v[50:51], 0
	v_mov_b64_e32 v[52:53], 0
	v_mov_b64_e32 v[54:55], 0
	v_mov_b64_e32 v[56:57], 0
	v_mov_b64_e32 v[58:59], 0
	v_mov_b64_e32 v[60:61], 0
	v_mov_b64_e32 v[62:63], 0
	v_mov_b64_e32 v[64:65], 0
	v_mov_b64_e32 v[66:67], 0
	v_mov_b64_e32 v[68:69], 0
	v_mov_b64_e32 v[70:71], 0
	v_mov_b64_e32 v[72:73], 0
	v_mov_b64_e32 v[74:75], 0
	v_mov_b64_e32 v[76:77], 0
	v_mov_b64_e32 v[78:79], 0
	v_mov_b64_e32 v[80:81], 0
	v_mov_b64_e32 v[82:83], 0
	v_mov_b64_e32 v[84:85], 0
	v_mov_b64_e32 v[86:87], 0
	v_mov_b64_e32 v[88:89], 0
	v_mov_b64_e32 v[90:91], 0
	v_mov_b64_e32 v[92:93], 0
	v_mov_b64_e32 v[94:95], 0
	v_mov_b64_e32 v[96:97], 0
	v_mov_b64_e32 v[98:99], 0
	v_mov_b64_e32 v[100:101], 0
	v_mov_b64_e32 v[102:103], 0
	v_mov_b64_e32 v[104:105], 0
	v_mov_b64_e32 v[106:107], 0
	v_mov_b64_e32 v[108:109], 0
	v_mov_b64_e32 v[110:111], 0
	v_mov_b64_e32 v[112:113], 0
	v_mov_b64_e32 v[114:115], 0
	v_mov_b64_e32 v[116:117], 0
	v_mov_b64_e32 v[118:119], 0
	v_mov_b64_e32 v[120:121], 0
	v_mov_b64_e32 v[122:123], 0
	v_mov_b64_e32 v[124:125], 0
	v_mov_b64_e32 v[126:127], 0
	v_mov_b64_e32 v[128:129], 0
	s_barrier
	s_branch .LBB0_1505

; #define PG8_STAGE(bufoff, gbase, voff) do { _Pragma("unroll") for (int _i = 0; _i < 2; ++_i) \
;         __builtin_amdgcn_global_load_lds((const unsigned*)((const char*)(gbase) + (voff)[_i]), (PG8_LAS unsigned*)(lds + (bufoff) + ldsw + _i * 8192), 16, 0, 0); } while (0)
; #define PG8_WAIT_V(n) asm volatile("s_waitcnt vmcnt(" #n ")" ::: "memory")
; #define PG8_BAR __builtin_amdgcn_s_barrier()
; template <class Epi, class Sched, bool ALIGN_EPI = false, bool SP2 = false>
; __device__ __forceinline__ void gemm_phase(PG8_LAS unsigned char* lds, const Gemm g, const Sched& S, const Epi& E, const int wave_id) {
;     ...
;     f32x4 acc[2][2][4][2];
; #pragma unroll
;     for (int a = 0; a < 2; ++a)
; #pragma unroll
;         for (int b = 0; b < 2; ++b)
; #pragma unroll
;             for (int m = 0; m < 4; ++m)
; #pragma unroll
;                 for (int n = 0; n < 2; ++n) acc[a][b][m][n] = (f32x4){0.f, 0.f, 0.f, 0.f};
;     bf16x8 At[4][2], B0[2][2], B1[2][2];
;     const char* cA = (const char*)g.A + (size_t)cur.pm * tstep; const char* cB = (const char*)g.Bt + (size_t)cur.pn * tstep;
;     S.a_ready(cur);
;     if constexpr (SP2) {
;         PG8_STAGE(PG8_SB(0, 0), cB, voffB); PG8_STAGE(PG8_SB(0, 1), cB + hstep, voffB); PG8_STAGE(PG8_SA(0, 0), cA, voffA); PG8_STAGE(PG8_SA(0, 1), cA + hstep, voffA);
;         if (wr == 1) PG8_BAR;
;         PG8_WAIT_V(2); PG8_BAR;
;         PG8_STAGE(PG8_SB(1, 0), cB + kstep, voffB); PG8_STAGE(PG8_SA(1, 0), cA + kstep, voffA); PG8_STAGE(PG8_SB(1, 1), cB + hstep + kstep, voffB);
;         PG8_WAIT_V(6); PG8_BAR;
.LBB0_1533:
	v_mov_b32_e32 v133, v0
	v_lshl_add_u64 v[10:11], s[18:19], 0, v[132:133]
	v_mov_b32_e32 v137, v0
	v_and_b32_e32 v1, 15, v6
	v_lshl_add_u64 v[12:13], s[18:19], 0, v[136:137]
	v_mov_b32_e32 v131, v0
	s_and_b32 s40, s8, 3
	v_bfe_u32 v162, v6, 4, 2
	v_lshlrev_b32_e32 v9, 6, v1
	v_lshlrev_b32_e32 v6, 2, v6
	s_add_i32 m0, s17, 0x18000
	v_lshl_add_u64 v[10:11], v[10:11], 0, s[64:65]
	v_lshl_add_u64 v[14:15], s[20:21], 0, v[130:131]
	v_mov_b32_e32 v135, v0
	v_lshl_or_b32 v9, v162, 4, v9
	v_and_b32_e32 v6, 32, v6
	s_lshl_b32 s9, s34, 13
	s_lshl_b32 s10, s40, 12
	s_waitcnt vmcnt(2)
	s_barrier
	global_load_lds_dwordx4 v[10:11], off
	v_lshl_add_u64 v[10:11], v[12:13], 0, s[64:65]
	s_add_i32 m0, s17, 0x1a000
	s_add_i32 s41, s17, 0x8000
	s_add_i32 s42, s17, 0xa000
	v_lshl_add_u64 v[16:17], s[20:21], 0, v[134:135]
	v_bitop3_b32 v163, v9, s10, v6 bitop3:0xde
	global_load_lds_dwordx4 v[10:11], off
	v_lshl_add_u64 v[10:11], v[14:15], 0, s[64:65]
	s_mov_b32 m0, s41
	s_add_u32 s10, s18, 0x40080
	global_load_lds_dwordx4 v[10:11], off
	v_lshl_add_u64 v[10:11], v[16:17], 0, s[64:65]
	s_mov_b32 m0, s42
	s_addc_u32 s11, s19, 0
	global_load_lds_dwordx4 v[10:11], off
	s_add_i32 m0, s17, 0x1c000
	v_lshl_add_u64 v[10:11], s[10:11], 0, v[132:133]
	global_load_lds_dwordx4 v[10:11], off
	v_lshl_add_u64 v[10:11], s[10:11], 0, v[136:137]
	s_add_i32 m0, s17, 0x1e000
	v_bitop3_b32 v6, v9, s9, v6 bitop3:0xde
	global_load_lds_dwordx4 v[10:11], off
	v_lshlrev_b32_e32 v9, 14, v5
	v_and_b32_e32 v9, 0xffff8000, v9
	v_lshl_add_u32 v7, v7, 11, v9
	v_and_b32_e32 v5, 1, v5
	v_lshl_or_b32 v5, v5, 6, v7
	v_lshl_add_u32 v138, v8, 1, v5
	v_lshlrev_b32_e32 v5, 14, v2
	v_and_b32_e32 v5, 0xffff8000, v5
	v_lshl_add_u32 v3, v3, 11, v5
	v_and_b32_e32 v2, 1, v2
	s_waitcnt vmcnt(6)
	v_lshl_or_b32 v2, v2, 6, v3
	s_cmp_lt_u32 s8, 4
	v_lshl_add_u32 v140, v4, 1, v2
	v_mov_b32_e32 v2, 0
	s_cselect_b64 s[24:25], -1, 0
	s_lshl_b32 s43, s36, 8
	v_mov_b32_e32 v139, v0
	v_mov_b32_e32 v141, v0
	s_mov_b32 s49, 0
	v_add_u32_e32 v164, 0, v6
	s_mov_b32 s50, s16
	v_mov_b32_e32 v3, v2
	v_mov_b64_e32 v[4:5], 0
	v_mov_b64_e32 v[6:7], 0
	v_mov_b64_e32 v[8:9], 0
	v_mov_b64_e32 v[10:11], 0
	v_mov_b64_e32 v[12:13], 0
	v_mov_b64_e32 v[14:15], 0
	v_mov_b64_e32 v[16:17], 0
	v_mov_b64_e32 v[18:19], 0
	v_mov_b64_e32 v[20:21], 0
	v_mov_b64_e32 v[22:23], 0
	v_mov_b64_e32 v[24:25], 0
	v_mov_b64_e32 v[26:27], 0
	v_mov_b64_e32 v[28:29], 0
	v_mov_b64_e32 v[30:31], 0
	v_mov_b64_e32 v[32:33], 0
	v_mov_b64_e32 v[34:35], 0
	v_mov_b64_e32 v[36:37], 0
	v_mov_b64_e32 v[38:39], 0
	v_mov_b64_e32 v[40:41], 0
	v_mov_b64_e32 v[42:43], 0
	v_mov_b64_e32 v[44:45], 0
	v_mov_b64_e32 v[46:47], 0
	v_mov_b64_e32 v[48:49], 0
	v_mov_b64_e32 v[50:51], 0
	v_mov_b64_e32 v[52:53], 0
	v_mov_b64_e32 v[54:55], 0
	v_mov_b64_e32 v[56:57], 0
	v_mov_b64_e32 v[58:59], 0
	v_mov_b64_e32 v[60:61], 0
	v_mov_b64_e32 v[62:63], 0
	v_mov_b64_e32 v[64:65], 0
	v_mov_b64_e32 v[66:67], 0
	v_mov_b64_e32 v[68:69], 0
	v_mov_b64_e32 v[70:71], 0
	v_mov_b64_e32 v[72:73], 0
	v_mov_b64_e32 v[74:75], 0
	v_mov_b64_e32 v[76:77], 0
	v_mov_b64_e32 v[78:79], 0
	v_mov_b64_e32 v[80:81], 0
	v_mov_b64_e32 v[82:83], 0
	v_mov_b64_e32 v[84:85], 0
	v_mov_b64_e32 v[86:87], 0
	v_mov_b64_e32 v[88:89], 0
	v_mov_b64_e32 v[90:91], 0
	v_mov_b64_e32 v[92:93], 0
	v_mov_b64_e32 v[94:95], 0
	v_mov_b64_e32 v[96:97], 0
	v_mov_b64_e32 v[98:99], 0
	v_mov_b64_e32 v[100:101], 0
	v_mov_b64_e32 v[102:103], 0
	v_mov_b64_e32 v[104:105], 0
	v_mov_b64_e32 v[106:107], 0
	v_mov_b64_e32 v[108:109], 0
	v_mov_b64_e32 v[110:111], 0
	v_mov_b64_e32 v[112:113], 0
	v_mov_b64_e32 v[114:115], 0
	v_mov_b64_e32 v[116:117], 0
	v_mov_b64_e32 v[118:119], 0
	v_mov_b64_e32 v[120:121], 0
	v_mov_b64_e32 v[122:123], 0
	v_mov_b64_e32 v[124:125], 0
	v_mov_b64_e32 v[126:127], 0
	v_mov_b64_e32 v[128:129], 0
	s_barrier
	s_branch .LBB0_1536

; template <class Epi, class Sched, bool ALIGN_EPI = false, bool SP2 = false>
; __device__ __forceinline__ void gemm_phase(PG8_LAS unsigned char* lds, const Gemm g, const Sched& S, const Epi& E, const int wave_id) {
;     ...
;         const bool keep_acc = E(acc, cur, wr, wc, fr, fq);
;         if (!has_next) break;
;         if (!keep_acc) {
; #pragma unroll
;         for (int a = 0; a < 2; ++a)
; #pragma unroll
;             for (int b = 0; b < 2; ++b)
; #pragma unroll
;                 for (int m = 0; m < 4; ++m)
; #pragma unroll
;                     for (int n = 0; n < 2; ++n) acc[a][b][m][n] = (f32x4){0.f, 0.f, 0.f, 0.f};
.LBB0_1605:
	s_andn2_b64 vcc, exec, s[26:27]
	s_cbranch_vccnz .LBB0_1607
	v_mov_b32_e32 v2, 0
	v_mov_b32_e32 v3, v2
	v_mov_b64_e32 v[4:5], 0
	v_mov_b64_e32 v[6:7], 0
	v_mov_b64_e32 v[8:9], 0
	v_mov_b64_e32 v[10:11], 0
	v_mov_b64_e32 v[12:13], 0
	v_mov_b64_e32 v[14:15], 0
	v_mov_b64_e32 v[16:17], 0
	v_mov_b64_e32 v[18:19], 0
	v_mov_b64_e32 v[20:21], 0
	v_mov_b64_e32 v[22:23], 0
	v_mov_b64_e32 v[24:25], 0
	v_mov_b64_e32 v[26:27], 0
	v_mov_b64_e32 v[28:29], 0
	v_mov_b64_e32 v[30:31], 0
	v_mov_b64_e32 v[32:33], 0
	v_mov_b64_e32 v[34:35], 0
	v_mov_b64_e32 v[36:37], 0
	v_mov_b64_e32 v[38:39], 0
	v_mov_b64_e32 v[40:41], 0
	v_mov_b64_e32 v[42:43], 0
	v_mov_b64_e32 v[44:45], 0
	v_mov_b64_e32 v[46:47], 0
	v_mov_b64_e32 v[48:49], 0
	v_mov_b64_e32 v[50:51], 0
	v_mov_b64_e32 v[52:53], 0
	v_mov_b64_e32 v[54:55], 0
	v_mov_b64_e32 v[56:57], 0
	v_mov_b64_e32 v[58:59], 0
	v_mov_b64_e32 v[60:61], 0
	v_mov_b64_e32 v[62:63], 0
	v_mov_b64_e32 v[64:65], 0
	v_mov_b64_e32 v[66:67], 0
	v_mov_b64_e32 v[68:69], 0
	v_mov_b64_e32 v[70:71], 0
	v_mov_b64_e32 v[72:73], 0
	v_mov_b64_e32 v[74:75], 0
	v_mov_b64_e32 v[76:77], 0
	v_mov_b64_e32 v[78:79], 0
	v_mov_b64_e32 v[80:81], 0
	v_mov_b64_e32 v[82:83], 0
	v_mov_b64_e32 v[84:85], 0
	v_mov_b64_e32 v[86:87], 0
	v_mov_b64_e32 v[88:89], 0
	v_mov_b64_e32 v[90:91], 0
	v_mov_b64_e32 v[92:93], 0
	v_mov_b64_e32 v[94:95], 0
	v_mov_b64_e32 v[96:97], 0
	v_mov_b64_e32 v[98:99], 0
	v_mov_b64_e32 v[100:101], 0
	v_mov_b64_e32 v[102:103], 0
	v_mov_b64_e32 v[104:105], 0
	v_mov_b64_e32 v[106:107], 0
	v_mov_b64_e32 v[108:109], 0
	v_mov_b64_e32 v[110:111], 0
	v_mov_b64_e32 v[112:113], 0
	v_mov_b64_e32 v[114:115], 0
	v_mov_b64_e32 v[116:117], 0
	v_mov_b64_e32 v[118:119], 0
	v_mov_b64_e32 v[120:121], 0
	v_mov_b64_e32 v[122:123], 0
	v_mov_b64_e32 v[124:125], 0
	v_mov_b64_e32 v[126:127], 0
	v_mov_b64_e32 v[128:129], 0

; #define PG8_STAGE(bufoff, gbase, voff) do { _Pragma("unroll") for (int _i = 0; _i < 2; ++_i) \
;         __builtin_amdgcn_global_load_lds((const unsigned*)((const char*)(gbase) + (voff)[_i]), (PG8_LAS unsigned*)(lds + (bufoff) + ldsw + _i * 8192), 16, 0, 0); } while (0)
; #define PG8_WAIT_V(n) asm volatile("s_waitcnt vmcnt(" #n ")" ::: "memory")
; #define PG8_BAR __builtin_amdgcn_s_barrier()
; template <class Epi, class Sched, bool ALIGN_EPI = false, bool SP2 = false>
; __device__ __forceinline__ void gemm_phase(PG8_LAS unsigned char* lds, const Gemm g, const Sched& S, const Epi& E, const int wave_id) {
;     ...
;     f32x4 acc[2][2][4][2];
; #pragma unroll
;     for (int a = 0; a < 2; ++a)
; #pragma unroll
;         for (int b = 0; b < 2; ++b)
; #pragma unroll
;             for (int m = 0; m < 4; ++m)
; #pragma unroll
;                 for (int n = 0; n < 2; ++n) acc[a][b][m][n] = (f32x4){0.f, 0.f, 0.f, 0.f};
;     bf16x8 At[4][2], B0[2][2], B1[2][2];
;     const char* cA = (const char*)g.A + (size_t)cur.pm * tstep; const char* cB = (const char*)g.Bt + (size_t)cur.pn * tstep;
;     S.a_ready(cur);
;     if constexpr (SP2) {
;         PG8_STAGE(PG8_SB(0, 0), cB, voffB); PG8_STAGE(PG8_SB(0, 1), cB + hstep, voffB); PG8_STAGE(PG8_SA(0, 0), cA, voffA); PG8_STAGE(PG8_SA(0, 1), cA + hstep, voffA);
;         if (wr == 1) PG8_BAR;
;         PG8_WAIT_V(2); PG8_BAR;
;         PG8_STAGE(PG8_SB(1, 0), cB + kstep, voffB); PG8_STAGE(PG8_SA(1, 0), cA + kstep, voffA); PG8_STAGE(PG8_SB(1, 1), cB + hstep + kstep, voffB);
;         PG8_WAIT_V(6); PG8_BAR;
.LBB0_1675:
	v_mov_b32_e32 v133, v0
	v_and_b32_e32 v1, 15, v2
	v_lshl_add_u64 v[10:11], s[22:23], 0, v[132:133]
	v_mov_b32_e32 v137, v0
	v_bfe_u32 v162, v2, 4, 2
	v_lshlrev_b32_e32 v9, 6, v1
	v_lshlrev_b32_e32 v2, 2, v2
	v_lshl_add_u64 v[12:13], s[22:23], 0, v[136:137]
	v_mov_b32_e32 v131, v0
	s_and_b32 s42, s12, 3
	v_lshl_or_b32 v9, v162, 4, v9
	s_lshl_b32 s4, s36, 13
	v_and_b32_e32 v2, 32, v2
	s_add_i32 m0, s38, 0x18000
	v_lshl_add_u64 v[10:11], v[10:11], 0, s[64:65]
	v_lshl_add_u64 v[14:15], s[20:21], 0, v[130:131]
	v_mov_b32_e32 v135, v0
	v_bitop3_b32 v18, v9, s4, v2 bitop3:0xde
	s_lshl_b32 s4, s42, 12
	s_waitcnt vmcnt(2)
	s_barrier
	global_load_lds_dwordx4 v[10:11], off
	v_lshl_add_u64 v[10:11], v[12:13], 0, s[64:65]
	s_add_i32 m0, s38, 0x1a000
	s_add_i32 s43, s38, 0x8000
	s_add_i32 s49, s38, 0xa000
	v_lshl_add_u64 v[16:17], s[20:21], 0, v[134:135]
	v_bitop3_b32 v163, v9, s4, v2 bitop3:0xde
	global_load_lds_dwordx4 v[10:11], off
	v_lshl_add_u64 v[10:11], v[14:15], 0, s[64:65]
	s_mov_b32 m0, s43
	s_add_u32 s4, s22, 0x40080
	global_load_lds_dwordx4 v[10:11], off
	v_lshl_add_u64 v[10:11], v[16:17], 0, s[64:65]
	s_mov_b32 m0, s49
	s_addc_u32 s5, s23, 0
	global_load_lds_dwordx4 v[10:11], off
	s_add_i32 m0, s38, 0x1c000
	v_lshl_add_u64 v[10:11], s[4:5], 0, v[132:133]
	global_load_lds_dwordx4 v[10:11], off
	v_lshl_add_u64 v[10:11], s[4:5], 0, v[136:137]
	s_add_i32 m0, s38, 0x1e000
	v_lshlrev_b32_e32 v2, 14, v6
	global_load_lds_dwordx4 v[10:11], off
	v_and_b32_e32 v2, 0xffff8000, v2
	v_lshl_add_u32 v2, v7, 11, v2
	v_and_b32_e32 v6, 1, v6
	v_lshl_or_b32 v2, v6, 6, v2
	v_lshl_add_u32 v138, v8, 1, v2
	v_lshlrev_b32_e32 v2, 14, v3
	v_and_b32_e32 v2, 0xffff8000, v2
	v_lshl_add_u32 v2, v4, 11, v2
	v_and_b32_e32 v3, 1, v3
	s_waitcnt vmcnt(6)
	v_lshl_or_b32 v2, v3, 6, v2
	s_cmp_lt_u32 s12, 4
	v_lshl_add_u32 v140, v5, 1, v2
	v_mov_b32_e32 v2, 0
	s_cselect_b64 s[4:5], -1, 0
	s_ashr_i32 s50, s29, 31
	v_mov_b32_e32 v139, v0
	v_mov_b32_e32 v141, v0
	s_mov_b32 s24, 0
	v_add_u32_e32 v164, 0, v18
	v_mov_b32_e32 v3, v2
	v_mov_b64_e32 v[4:5], 0
	v_mov_b64_e32 v[6:7], 0
	v_mov_b64_e32 v[8:9], 0
	v_mov_b64_e32 v[10:11], 0
	v_mov_b64_e32 v[12:13], 0
	v_mov_b64_e32 v[14:15], 0
	v_mov_b64_e32 v[16:17], 0
	v_mov_b64_e32 v[18:19], 0
	v_mov_b64_e32 v[20:21], 0
	v_mov_b64_e32 v[22:23], 0
	v_mov_b64_e32 v[24:25], 0
	v_mov_b64_e32 v[26:27], 0
	v_mov_b64_e32 v[28:29], 0
	v_mov_b64_e32 v[30:31], 0
	v_mov_b64_e32 v[32:33], 0
	v_mov_b64_e32 v[34:35], 0
	v_mov_b64_e32 v[36:37], 0
	v_mov_b64_e32 v[38:39], 0
	v_mov_b64_e32 v[40:41], 0
	v_mov_b64_e32 v[42:43], 0
	v_mov_b64_e32 v[44:45], 0
	v_mov_b64_e32 v[46:47], 0
	v_mov_b64_e32 v[48:49], 0
	v_mov_b64_e32 v[50:51], 0
	v_mov_b64_e32 v[52:53], 0
	v_mov_b64_e32 v[54:55], 0
	v_mov_b64_e32 v[56:57], 0
	v_mov_b64_e32 v[58:59], 0
	v_mov_b64_e32 v[60:61], 0
	v_mov_b64_e32 v[62:63], 0
	v_mov_b64_e32 v[64:65], 0
	v_mov_b64_e32 v[66:67], 0
	v_mov_b64_e32 v[68:69], 0
	v_mov_b64_e32 v[70:71], 0
	v_mov_b64_e32 v[72:73], 0
	v_mov_b64_e32 v[74:75], 0
	v_mov_b64_e32 v[76:77], 0
	v_mov_b64_e32 v[78:79], 0
	v_mov_b64_e32 v[80:81], 0
	v_mov_b64_e32 v[82:83], 0
	v_mov_b64_e32 v[84:85], 0
	v_mov_b64_e32 v[86:87], 0
	v_mov_b64_e32 v[88:89], 0
	v_mov_b64_e32 v[90:91], 0
	v_mov_b64_e32 v[92:93], 0
	v_mov_b64_e32 v[94:95], 0
	v_mov_b64_e32 v[96:97], 0
	v_mov_b64_e32 v[98:99], 0
	v_mov_b64_e32 v[100:101], 0
	v_mov_b64_e32 v[102:103], 0
	v_mov_b64_e32 v[104:105], 0
	v_mov_b64_e32 v[106:107], 0
	v_mov_b64_e32 v[108:109], 0
	v_mov_b64_e32 v[110:111], 0
	v_mov_b64_e32 v[112:113], 0
	v_mov_b64_e32 v[114:115], 0
	v_mov_b64_e32 v[116:117], 0
	v_mov_b64_e32 v[118:119], 0
	v_mov_b64_e32 v[120:121], 0
	v_mov_b64_e32 v[122:123], 0
	v_mov_b64_e32 v[124:125], 0
	v_mov_b64_e32 v[126:127], 0
	v_mov_b64_e32 v[128:129], 0
	s_barrier
	s_branch .LBB0_1678

; template <class Epi, class Sched, bool ALIGN_EPI = false, bool SP2 = false>
; __device__ __forceinline__ void gemm_phase(PG8_LAS unsigned char* lds, const Gemm g, const Sched& S, const Epi& E, const int wave_id) {
;     ...
;         const bool keep_acc = E(acc, cur, wr, wc, fr, fq);
;         if (!has_next) break;
;         if (!keep_acc) {
; #pragma unroll
;         for (int a = 0; a < 2; ++a)
; #pragma unroll
;             for (int b = 0; b < 2; ++b)
; #pragma unroll
;                 for (int m = 0; m < 4; ++m)
; #pragma unroll
;                     for (int n = 0; n < 2; ++n) acc[a][b][m][n] = (f32x4){0.f, 0.f, 0.f, 0.f};
.Lgate_epi_done:
.LBB0_1752:
	s_andn2_b64 vcc, exec, s[6:7]
	s_mov_b64 s[6:7], -1
	s_cbranch_vccnz .LBB0_1677
	s_andn2_b64 vcc, exec, s[20:21]
	s_cbranch_vccnz .LBB0_1755
	v_mov_b32_e32 v2, 0
	v_mov_b32_e32 v3, v2
	v_mov_b64_e32 v[4:5], 0
	v_mov_b64_e32 v[6:7], 0
	v_mov_b64_e32 v[8:9], 0
	v_mov_b64_e32 v[10:11], 0
	v_mov_b64_e32 v[12:13], 0
	v_mov_b64_e32 v[14:15], 0
	v_mov_b64_e32 v[16:17], 0
	v_mov_b64_e32 v[18:19], 0
	v_mov_b64_e32 v[20:21], 0
	v_mov_b64_e32 v[22:23], 0
	v_mov_b64_e32 v[24:25], 0
	v_mov_b64_e32 v[26:27], 0
	v_mov_b64_e32 v[28:29], 0
	v_mov_b64_e32 v[30:31], 0
	v_mov_b64_e32 v[32:33], 0
	v_mov_b64_e32 v[34:35], 0
	v_mov_b64_e32 v[36:37], 0
	v_mov_b64_e32 v[38:39], 0
	v_mov_b64_e32 v[40:41], 0
	v_mov_b64_e32 v[42:43], 0
	v_mov_b64_e32 v[44:45], 0
	v_mov_b64_e32 v[46:47], 0
	v_mov_b64_e32 v[48:49], 0
	v_mov_b64_e32 v[50:51], 0
	v_mov_b64_e32 v[52:53], 0
	v_mov_b64_e32 v[54:55], 0
	v_mov_b64_e32 v[56:57], 0
	v_mov_b64_e32 v[58:59], 0
	v_mov_b64_e32 v[60:61], 0
	v_mov_b64_e32 v[62:63], 0
	v_mov_b64_e32 v[64:65], 0
	v_mov_b64_e32 v[66:67], 0
	v_mov_b64_e32 v[68:69], 0
	v_mov_b64_e32 v[70:71], 0
	v_mov_b64_e32 v[72:73], 0
	v_mov_b64_e32 v[74:75], 0
	v_mov_b64_e32 v[76:77], 0
	v_mov_b64_e32 v[78:79], 0
	v_mov_b64_e32 v[80:81], 0
	v_mov_b64_e32 v[82:83], 0
	v_mov_b64_e32 v[84:85], 0
	v_mov_b64_e32 v[86:87], 0
	v_mov_b64_e32 v[88:89], 0
	v_mov_b64_e32 v[90:91], 0
	v_mov_b64_e32 v[92:93], 0
	v_mov_b64_e32 v[94:95], 0
	v_mov_b64_e32 v[96:97], 0
	v_mov_b64_e32 v[98:99], 0
	v_mov_b64_e32 v[100:101], 0
	v_mov_b64_e32 v[102:103], 0
	v_mov_b64_e32 v[104:105], 0
	v_mov_b64_e32 v[106:107], 0
	v_mov_b64_e32 v[108:109], 0
	v_mov_b64_e32 v[110:111], 0
	v_mov_b64_e32 v[112:113], 0
	v_mov_b64_e32 v[114:115], 0
	v_mov_b64_e32 v[116:117], 0
	v_mov_b64_e32 v[118:119], 0
	v_mov_b64_e32 v[120:121], 0
	v_mov_b64_e32 v[122:123], 0
	v_mov_b64_e32 v[124:125], 0
	v_mov_b64_e32 v[126:127], 0
	v_mov_b64_e32 v[128:129], 0

;     __device__ __forceinline__ bool next(int i, Unit& u) const { Unit t; if (!pg8::StaticOrder::next(i / 3, t)) return false; const int k = i % 3; u.pm = t.pm + k * NPANEL; u.pn = t.pn + 4 * k; return true; }
;     __device__ __forceinline__ bool next(int i, Unit& u) const { if (i > 0 || c >= 8) return false; u.pm = 256 + (c >> 2); u.pn = c & 3; return true; }
;     __device__ __forceinline__ bool next(int i, Unit& u) const { if (i > 0 || c >= 16) return false; u.pm = 256 + ((c >> 2) & 1); u.pn = c & 3; return true; }
;     __device__ __forceinline__ bool next(int i, Unit& u) const { if (i > 2) return false; u.pm = 256 + (c >> 2) + i * NPANEL; u.pn = (c & 3) + 4 * i; return true; }
;     __device__ __forceinline__ bool next(int i, Unit& u) const { if (i > 0) return false; const int p = c >= 22 ? 1 : 0; u.pm = 256 + p; u.pn = c - 22 * p; return true; }
; template <class Epi, class Sched, bool ALIGN_EPI = false, bool SP2 = false>
; __device__ __forceinline__ void gemm_phase(PG8_LAS unsigned char* lds, const Gemm g, const Sched& S, const Epi& E, const int wave_id) {
;     ...
;         const bool has_next = S.next(ui + 1, nxt);
;         const char* nA = has_next ? (const char*)g.A + (size_t)nxt.pm * tstep : cA; const char* nB = has_next ? (const char*)g.Bt + (size_t)nxt.pn * tstep : cB;
;         for (int t = 0; t < nt; t += 2) {
;             const bool last = (t == nt - 2);
;             const char* a1 = cA + (size_t)(t + 1) * kstep;
;             const char* a2 = last ? nA : cA + (size_t)(t + 2) * kstep; const char* b2 = last ? nB : cB + (size_t)(t + 2) * kstep;
;             const char* a3 = a2 + kstep; const char* b3 = b2 + kstep;
;             if (last && has_next) S.a_ready(nxt);
;             if constexpr (SP2) {
;             int tz_ = __builtin_amdgcn_readfirstlane(t | (ui > 0 ? 0 : 1)); asm volatile("" : "+s"(tz_));
;     ...
;         if (!keep_acc) {
; #pragma unroll
;         for (int a = 0; a < 2; ++a)
; #pragma unroll
;             for (int b = 0; b < 2; ++b)
; #pragma unroll
;                 for (int m = 0; m < 4; ++m)
; #pragma unroll
;                     for (int n = 0; n < 2; ++n) acc[a][b][m][n] = (f32x4){0.f, 0.f, 0.f, 0.f};
.LBB0_1820:
	s_ashr_i32 s11, s10, 31
	s_lshl_b64 s[12:13], s[10:11], 19
	s_add_u32 s12, s31, s12
	s_addc_u32 s13, s34, s13
	s_and_b64 s[14:15], s[6:7], exec
	s_cselect_b32 s11, s13, s19
	s_cselect_b32 s63, s12, s18
	s_ashr_i32 s9, s8, 31
	s_lshl_b64 s[14:15], s[8:9], 19
	s_add_u32 s14, s35, s14
	s_addc_u32 s15, s36, s15
	s_and_b64 s[24:25], s[6:7], exec
	s_cselect_b32 s9, s15, s21
	s_cselect_b32 s67, s14, s20
	s_cmp_eq_u32 s22, 0
	s_cselect_b64 s[22:23], -1, 0
	s_add_u32 s68, s20, 0x100
	s_addc_u32 s69, s21, 0
	s_add_u32 s20, s18, 0x40080
	s_addc_u32 s21, s19, 0
	v_mov_b32_e32 v2, 0
	v_cndmask_b32_e64 v248, 0, 1, s[22:23]
	v_lshl_add_u64 v[222:223], s[20:21], 0, v[218:219]
	v_lshl_add_u64 v[224:225], s[20:21], 0, v[220:221]
	s_mov_b32 s74, -2
	s_mov_b64 s[20:21], 0
	v_mov_b32_e32 v3, v2
	v_mov_b64_e32 v[4:5], 0
	v_mov_b64_e32 v[6:7], 0
	v_mov_b64_e32 v[8:9], 0
	v_mov_b64_e32 v[10:11], 0
	v_mov_b64_e32 v[12:13], 0
	v_mov_b64_e32 v[14:15], 0
	v_mov_b64_e32 v[16:17], 0
	v_mov_b64_e32 v[18:19], 0
	v_mov_b64_e32 v[20:21], 0
	v_mov_b64_e32 v[22:23], 0
	v_mov_b64_e32 v[24:25], 0
	v_mov_b64_e32 v[26:27], 0
	v_mov_b64_e32 v[28:29], 0
	v_mov_b64_e32 v[30:31], 0
	v_mov_b64_e32 v[32:33], 0
	v_mov_b64_e32 v[34:35], 0
	v_mov_b64_e32 v[36:37], 0
	v_mov_b64_e32 v[38:39], 0
	v_mov_b64_e32 v[40:41], 0
	v_mov_b64_e32 v[42:43], 0
	v_mov_b64_e32 v[44:45], 0
	v_mov_b64_e32 v[46:47], 0
	v_mov_b64_e32 v[48:49], 0
	v_mov_b64_e32 v[50:51], 0
	v_mov_b64_e32 v[52:53], 0
	v_mov_b64_e32 v[54:55], 0
	v_mov_b64_e32 v[56:57], 0
	v_mov_b64_e32 v[58:59], 0
	v_mov_b64_e32 v[60:61], 0
	v_mov_b64_e32 v[62:63], 0
	v_mov_b64_e32 v[64:65], 0
	v_mov_b64_e32 v[66:67], 0
	v_mov_b64_e32 v[68:69], 0
	v_mov_b64_e32 v[70:71], 0
	v_mov_b64_e32 v[72:73], 0
	v_mov_b64_e32 v[74:75], 0
	v_mov_b64_e32 v[76:77], 0
	v_mov_b64_e32 v[78:79], 0
	v_mov_b64_e32 v[80:81], 0
	v_mov_b64_e32 v[82:83], 0
	v_mov_b64_e32 v[84:85], 0
	v_mov_b64_e32 v[86:87], 0
	v_mov_b64_e32 v[88:89], 0
	v_mov_b64_e32 v[90:91], 0
	v_mov_b64_e32 v[92:93], 0
	v_mov_b64_e32 v[94:95], 0
	v_mov_b64_e32 v[96:97], 0
	v_mov_b64_e32 v[98:99], 0
	v_mov_b64_e32 v[100:101], 0
	v_mov_b64_e32 v[102:103], 0
	v_mov_b64_e32 v[104:105], 0
	v_mov_b64_e32 v[106:107], 0
	v_mov_b64_e32 v[108:109], 0
	v_mov_b64_e32 v[110:111], 0
	v_mov_b64_e32 v[112:113], 0
	v_mov_b64_e32 v[114:115], 0
	v_mov_b64_e32 v[116:117], 0
	v_mov_b64_e32 v[118:119], 0
	v_mov_b64_e32 v[120:121], 0
	v_mov_b64_e32 v[122:123], 0
	v_mov_b64_e32 v[124:125], 0
	v_mov_b64_e32 v[126:127], 0
	v_mov_b64_e32 v[128:129], 0
	s_branch .LBB0_1822

; #define PG8_STAGE(bufoff, gbase, voff) do { _Pragma("unroll") for (int _i = 0; _i < 2; ++_i) \
;         __builtin_amdgcn_global_load_lds((const unsigned*)((const char*)(gbase) + (voff)[_i]), (PG8_LAS unsigned*)(lds + (bufoff) + ldsw + _i * 8192), 16, 0, 0); } while (0)
; #define PG8_WAIT_V(n) asm volatile("s_waitcnt vmcnt(" #n ")" ::: "memory")
; #define PG8_BAR __builtin_amdgcn_s_barrier()
; template <class Epi, class Sched, bool ALIGN_EPI = false, bool SP2 = false>
; __device__ __forceinline__ void gemm_phase(PG8_LAS unsigned char* lds, const Gemm g, const Sched& S, const Epi& E, const int wave_id) {
;     ...
;     f32x4 acc[2][2][4][2];
; #pragma unroll
;     for (int a = 0; a < 2; ++a)
; #pragma unroll
;         for (int b = 0; b < 2; ++b)
; #pragma unroll
;             for (int m = 0; m < 4; ++m)
; #pragma unroll
;                 for (int n = 0; n < 2; ++n) acc[a][b][m][n] = (f32x4){0.f, 0.f, 0.f, 0.f};
;     bf16x8 At[4][2], B0[2][2], B1[2][2];
;     const char* cA = (const char*)g.A + (size_t)cur.pm * tstep; const char* cB = (const char*)g.Bt + (size_t)cur.pn * tstep;
;     S.a_ready(cur);
;     if constexpr (SP2) {
;         PG8_STAGE(PG8_SB(0, 0), cB, voffB); PG8_STAGE(PG8_SB(0, 1), cB + hstep, voffB); PG8_STAGE(PG8_SA(0, 0), cA, voffA); PG8_STAGE(PG8_SA(0, 1), cA + hstep, voffA);
;         if (wr == 1) PG8_BAR;
;         PG8_WAIT_V(2); PG8_BAR;
;         PG8_STAGE(PG8_SB(1, 0), cB + kstep, voffB); PG8_STAGE(PG8_SA(1, 0), cA + kstep, voffA); PG8_STAGE(PG8_SB(1, 1), cB + hstep + kstep, voffB);
;         PG8_WAIT_V(6); PG8_BAR;
.LBB0_1888:
	v_and_b32_e32 v1, 15, v14
	s_and_b32 s27, s18, 3
	v_bfe_u32 v230, v14, 4, 2
	v_lshlrev_b32_e32 v17, 6, v1
	v_lshlrev_b32_e32 v14, 2, v14
	v_lshl_or_b32 v17, v230, 4, v17
	v_and_b32_e32 v14, 32, v14
	s_lshl_b32 s30, s27, 12
	s_add_i32 m0, s5, 0x18000
	v_lshl_add_u64 v[8:9], v[8:9], 0, s[64:65]
	s_lshl_b32 s17, s20, 13
	v_bitop3_b32 v231, v17, s30, v14 bitop3:0xde
	s_waitcnt vmcnt(2)
	s_barrier
	global_load_lds_dwordx4 v[8:9], off
	v_lshl_add_u64 v[6:7], v[6:7], 0, s[64:65]
	s_add_i32 m0, s5, 0x1a000
	s_add_i32 s30, s5, 0x8000
	s_add_i32 s31, s5, 0xa000
	global_load_lds_dwordx4 v[6:7], off
	v_lshl_add_u64 v[4:5], v[4:5], 0, s[64:65]
	s_mov_b32 m0, s30
	s_add_u32 s34, s6, 0x40080
	global_load_lds_dwordx4 v[4:5], off
	v_lshl_add_u64 v[2:3], v[2:3], 0, s[64:65]
	s_mov_b32 m0, s31
	s_addc_u32 s35, s7, 0
	global_load_lds_dwordx4 v[2:3], off
	s_add_i32 m0, s5, 0x1c000
	v_lshl_add_u64 v[2:3], s[34:35], 0, v[212:213]
	global_load_lds_dwordx4 v[2:3], off
	v_lshl_add_u64 v[2:3], s[34:35], 0, v[216:217]
	s_add_i32 m0, s5, 0x1e000
	v_bitop3_b32 v14, v17, s17, v14 bitop3:0xde
	global_load_lds_dwordx4 v[2:3], off
	v_readlane_b32 s17, v254, 57
	s_add_u32 s14, s17, s14
	s_addc_u32 s15, 0, s15
	s_add_u32 s12, s12, s14
	s_addc_u32 s13, s13, s15
	s_add_u32 s34, s12, 0x9a040100
	s_addc_u32 s35, s13, 0
	v_lshlrev_b32_e32 v2, 14, v13
	v_and_b32_e32 v2, 0xffff8000, v2
	s_add_u32 s36, s10, s16
	v_lshl_add_u32 v2, v15, 11, v2
	v_and_b32_e32 v3, 1, v13
	s_addc_u32 s37, s11, 0
	v_lshl_or_b32 v2, v3, 6, v2
	s_add_u32 s10, s36, 0x8240080
	v_lshl_add_u32 v2, v16, 1, v2
	v_mov_b32_e32 v3, v0
	s_addc_u32 s11, s37, 0
	v_lshl_add_u64 v[218:219], s[10:11], 0, v[2:3]
	v_lshlrev_b32_e32 v2, 14, v10
	v_and_b32_e32 v2, 0xffff8000, v2
	v_lshl_add_u32 v2, v11, 11, v2
	v_and_b32_e32 v3, 1, v10
	v_lshl_or_b32 v2, v3, 6, v2
	s_waitcnt vmcnt(6)
	v_lshl_add_u32 v2, v12, 1, v2
	v_mov_b32_e32 v3, v0
	v_lshl_add_u64 v[220:221], s[10:11], 0, v[2:3]
	v_mov_b32_e32 v2, 0
	s_mov_b32 s38, -2
	s_mov_b64 s[10:11], 0
	v_add_u32_e32 v232, 0, v14
	v_mov_b32_e32 v3, v2
	v_mov_b64_e32 v[4:5], 0
	v_mov_b64_e32 v[6:7], 0
	v_mov_b64_e32 v[8:9], 0
	v_mov_b64_e32 v[10:11], 0
	v_mov_b64_e32 v[12:13], 0
	v_mov_b64_e32 v[14:15], 0
	v_mov_b64_e32 v[16:17], 0
	v_mov_b64_e32 v[18:19], 0
	v_mov_b64_e32 v[20:21], 0
	v_mov_b64_e32 v[22:23], 0
	v_mov_b64_e32 v[24:25], 0
	v_mov_b64_e32 v[26:27], 0
	v_mov_b64_e32 v[28:29], 0
	v_mov_b64_e32 v[30:31], 0
	v_mov_b64_e32 v[32:33], 0
	v_mov_b64_e32 v[34:35], 0
	v_mov_b64_e32 v[36:37], 0
	v_mov_b64_e32 v[38:39], 0
	v_mov_b64_e32 v[40:41], 0
	v_mov_b64_e32 v[42:43], 0
	v_mov_b64_e32 v[44:45], 0
	v_mov_b64_e32 v[46:47], 0
	v_mov_b64_e32 v[48:49], 0
	v_mov_b64_e32 v[50:51], 0
	v_mov_b64_e32 v[52:53], 0
	v_mov_b64_e32 v[54:55], 0
	v_mov_b64_e32 v[56:57], 0
	v_mov_b64_e32 v[58:59], 0
	v_mov_b64_e32 v[60:61], 0
	v_mov_b64_e32 v[62:63], 0
	v_mov_b64_e32 v[64:65], 0
	v_mov_b64_e32 v[66:67], 0
	v_mov_b64_e32 v[68:69], 0
	v_mov_b64_e32 v[70:71], 0
	v_mov_b64_e32 v[72:73], 0
	v_mov_b64_e32 v[74:75], 0
	v_mov_b64_e32 v[76:77], 0
	v_mov_b64_e32 v[78:79], 0
	v_mov_b64_e32 v[80:81], 0
	v_mov_b64_e32 v[82:83], 0
	v_mov_b64_e32 v[84:85], 0
	v_mov_b64_e32 v[86:87], 0
	v_mov_b64_e32 v[88:89], 0
	v_mov_b64_e32 v[90:91], 0
	v_mov_b64_e32 v[92:93], 0
	v_mov_b64_e32 v[94:95], 0
	v_mov_b64_e32 v[96:97], 0
	v_mov_b64_e32 v[98:99], 0
	v_mov_b64_e32 v[100:101], 0
	v_mov_b64_e32 v[102:103], 0
	v_mov_b64_e32 v[104:105], 0
	v_mov_b64_e32 v[106:107], 0
	v_mov_b64_e32 v[108:109], 0
	v_mov_b64_e32 v[110:111], 0
	v_mov_b64_e32 v[112:113], 0
	v_mov_b64_e32 v[114:115], 0
	v_mov_b64_e32 v[116:117], 0
	v_mov_b64_e32 v[118:119], 0
	v_mov_b64_e32 v[120:121], 0
	v_mov_b64_e32 v[122:123], 0
	v_mov_b64_e32 v[124:125], 0
	v_mov_b64_e32 v[126:127], 0
	v_mov_b64_e32 v[128:129], 0
	s_barrier
	s_branch .LBB0_1890

;     __device__ __forceinline__ bool next(int i, Unit& u) const { Unit t; if (!pg8::StaticOrder::next(i / 3, t)) return false; const int k = i % 3; u.pm = t.pm + k * NPANEL; u.pn = t.pn + 4 * k; return true; }
;     __device__ __forceinline__ bool next(int i, Unit& u) const { if (i > 0 || c >= 8) return false; u.pm = 256 + (c >> 2); u.pn = c & 3; return true; }
;     __device__ __forceinline__ bool next(int i, Unit& u) const { if (i > 0 || c >= 16) return false; u.pm = 256 + ((c >> 2) & 1); u.pn = c & 3; return true; }
;     __device__ __forceinline__ bool next(int i, Unit& u) const { if (i > 2) return false; u.pm = 256 + (c >> 2) + i * NPANEL; u.pn = (c & 3) + 4 * i; return true; }
;     __device__ __forceinline__ bool next(int i, Unit& u) const { if (i > 0) return false; const int p = c >= 22 ? 1 : 0; u.pm = 256 + p; u.pn = c - 22 * p; return true; }
; template <class Epi, class Sched, bool ALIGN_EPI = false, bool SP2 = false>
; __device__ __forceinline__ void gemm_phase(PG8_LAS unsigned char* lds, const Gemm g, const Sched& S, const Epi& E, const int wave_id) {
;     ...
;         const bool has_next = S.next(ui + 1, nxt);
;         const char* nA = has_next ? (const char*)g.A + (size_t)nxt.pm * tstep : cA; const char* nB = has_next ? (const char*)g.Bt + (size_t)nxt.pn * tstep : cB;
;         for (int t = 0; t < nt; t += 2) {
;             const bool last = (t == nt - 2);
;             const char* a1 = cA + (size_t)(t + 1) * kstep;
;             const char* a2 = last ? nA : cA + (size_t)(t + 2) * kstep; const char* b2 = last ? nB : cB + (size_t)(t + 2) * kstep;
;             const char* a3 = a2 + kstep; const char* b3 = b2 + kstep;
;             if (last && has_next) S.a_ready(nxt);
;             if constexpr (SP2) {
;             int tz_ = __builtin_amdgcn_readfirstlane(t | (ui > 0 ? 0 : 1)); asm volatile("" : "+s"(tz_));
;     ...
;         if (!keep_acc) {
; #pragma unroll
;         for (int a = 0; a < 2; ++a)
; #pragma unroll
;             for (int b = 0; b < 2; ++b)
; #pragma unroll
;                 for (int m = 0; m < 4; ++m)
; #pragma unroll
;                     for (int n = 0; n < 2; ++n) acc[a][b][m][n] = (f32x4){0.f, 0.f, 0.f, 0.f};
.LBB0_1951:
	s_ashr_i32 s13, s12, 31
	s_lshl_b64 s[14:15], s[12:13], 19
	s_add_u32 s14, s34, s14
	s_addc_u32 s15, s35, s15
	s_and_b64 s[16:17], s[6:7], exec
	s_cselect_b32 s13, s15, s21
	s_cselect_b32 s68, s14, s20
	s_ashr_i32 s11, s10, 31
	s_lshl_b64 s[16:17], s[10:11], 19
	s_add_u32 s16, s36, s16
	s_addc_u32 s17, s37, s17
	s_and_b64 s[26:27], s[6:7], exec
	s_cselect_b32 s11, s17, s23
	s_cselect_b32 s69, s16, s22
	s_cmp_eq_u32 s24, 0
	s_cselect_b64 s[24:25], -1, 0
	s_add_u32 s74, s22, 0x100
	s_addc_u32 s75, s23, 0
	s_add_u32 s22, s20, 0x40080
	s_addc_u32 s23, s21, 0
	v_mov_b32_e32 v2, 0
	v_cndmask_b32_e64 v248, 0, 1, s[24:25]
	v_lshl_add_u64 v[222:223], s[22:23], 0, v[218:219]
	v_lshl_add_u64 v[224:225], s[22:23], 0, v[220:221]
	s_mov_b32 s76, -2
	s_mov_b64 s[22:23], 0
	v_mov_b32_e32 v3, v2
	v_mov_b64_e32 v[4:5], 0
	v_mov_b64_e32 v[6:7], 0
	v_mov_b64_e32 v[8:9], 0
	v_mov_b64_e32 v[10:11], 0
	v_mov_b64_e32 v[12:13], 0
	v_mov_b64_e32 v[14:15], 0
	v_mov_b64_e32 v[16:17], 0
	v_mov_b64_e32 v[18:19], 0
	v_mov_b64_e32 v[20:21], 0
	v_mov_b64_e32 v[22:23], 0
	v_mov_b64_e32 v[24:25], 0
	v_mov_b64_e32 v[26:27], 0
	v_mov_b64_e32 v[28:29], 0
	v_mov_b64_e32 v[30:31], 0
	v_mov_b64_e32 v[32:33], 0
	v_mov_b64_e32 v[34:35], 0
	v_mov_b64_e32 v[36:37], 0
	v_mov_b64_e32 v[38:39], 0
	v_mov_b64_e32 v[40:41], 0
	v_mov_b64_e32 v[42:43], 0
	v_mov_b64_e32 v[44:45], 0
	v_mov_b64_e32 v[46:47], 0
	v_mov_b64_e32 v[48:49], 0
	v_mov_b64_e32 v[50:51], 0
	v_mov_b64_e32 v[52:53], 0
	v_mov_b64_e32 v[54:55], 0
	v_mov_b64_e32 v[56:57], 0
	v_mov_b64_e32 v[58:59], 0
	v_mov_b64_e32 v[60:61], 0
	v_mov_b64_e32 v[62:63], 0
	v_mov_b64_e32 v[64:65], 0
	v_mov_b64_e32 v[66:67], 0
	v_mov_b64_e32 v[68:69], 0
	v_mov_b64_e32 v[70:71], 0
	v_mov_b64_e32 v[72:73], 0
	v_mov_b64_e32 v[74:75], 0
	v_mov_b64_e32 v[76:77], 0
	v_mov_b64_e32 v[78:79], 0
	v_mov_b64_e32 v[80:81], 0
	v_mov_b64_e32 v[82:83], 0
	v_mov_b64_e32 v[84:85], 0
	v_mov_b64_e32 v[86:87], 0
	v_mov_b64_e32 v[88:89], 0
	v_mov_b64_e32 v[90:91], 0
	v_mov_b64_e32 v[92:93], 0
	v_mov_b64_e32 v[94:95], 0
	v_mov_b64_e32 v[96:97], 0
	v_mov_b64_e32 v[98:99], 0
	v_mov_b64_e32 v[100:101], 0
	v_mov_b64_e32 v[102:103], 0
	v_mov_b64_e32 v[104:105], 0
	v_mov_b64_e32 v[106:107], 0
	v_mov_b64_e32 v[108:109], 0
	v_mov_b64_e32 v[110:111], 0
	v_mov_b64_e32 v[112:113], 0
	v_mov_b64_e32 v[114:115], 0
	v_mov_b64_e32 v[116:117], 0
	v_mov_b64_e32 v[118:119], 0
	v_mov_b64_e32 v[120:121], 0
	v_mov_b64_e32 v[122:123], 0
	v_mov_b64_e32 v[124:125], 0
	v_mov_b64_e32 v[126:127], 0
	v_mov_b64_e32 v[128:129], 0
	s_branch .LBB0_1953

; #define PG8_STAGE(bufoff, gbase, voff) do { _Pragma("unroll") for (int _i = 0; _i < 2; ++_i) \
;         __builtin_amdgcn_global_load_lds((const unsigned*)((const char*)(gbase) + (voff)[_i]), (PG8_LAS unsigned*)(lds + (bufoff) + ldsw + _i * 8192), 16, 0, 0); } while (0)
; #define PG8_WAIT_V(n) asm volatile("s_waitcnt vmcnt(" #n ")" ::: "memory")
; #define PG8_BAR __builtin_amdgcn_s_barrier()
; template <class Epi, class Sched, bool ALIGN_EPI = false, bool SP2 = false>
; __device__ __forceinline__ void gemm_phase(PG8_LAS unsigned char* lds, const Gemm g, const Sched& S, const Epi& E, const int wave_id) {
;     ...
;     f32x4 acc[2][2][4][2];
; #pragma unroll
;     for (int a = 0; a < 2; ++a)
; #pragma unroll
;         for (int b = 0; b < 2; ++b)
; #pragma unroll
;             for (int m = 0; m < 4; ++m)
; #pragma unroll
;                 for (int n = 0; n < 2; ++n) acc[a][b][m][n] = (f32x4){0.f, 0.f, 0.f, 0.f};
;     bf16x8 At[4][2], B0[2][2], B1[2][2];
;     const char* cA = (const char*)g.A + (size_t)cur.pm * tstep; const char* cB = (const char*)g.Bt + (size_t)cur.pn * tstep;
;     S.a_ready(cur);
;     if constexpr (SP2) {
;         PG8_STAGE(PG8_SB(0, 0), cB, voffB); PG8_STAGE(PG8_SB(0, 1), cB + hstep, voffB); PG8_STAGE(PG8_SA(0, 0), cA, voffA); PG8_STAGE(PG8_SA(0, 1), cA + hstep, voffA);
;         if (wr == 1) PG8_BAR;
;         PG8_WAIT_V(2); PG8_BAR;
;         PG8_STAGE(PG8_SB(1, 0), cB + kstep, voffB); PG8_STAGE(PG8_SA(1, 0), cA + kstep, voffA); PG8_STAGE(PG8_SB(1, 1), cB + hstep + kstep, voffB);
;         PG8_WAIT_V(6); PG8_BAR;
.LBB0_2109:
	v_and_b32_e32 v230, 15, v13
	v_bfe_u32 v1, v13, 4, 2
	v_lshlrev_b32_e32 v19, 6, v230
	v_lshlrev_b32_e32 v13, 2, v13
	s_and_b32 s27, s5, 3
	v_lshl_or_b32 v19, v1, 4, v19
	s_lshl_b32 s31, s19, 13
	v_and_b32_e32 v13, 32, v13
	v_bitop3_b32 v20, v19, s31, v13 bitop3:0xde
	s_lshl_b32 s31, s27, 12
	s_add_i32 m0, s22, 0x18000
	v_lshl_add_u64 v[8:9], v[8:9], 0, s[64:65]
	v_bitop3_b32 v231, v19, s31, v13 bitop3:0xde
	s_waitcnt vmcnt(2)
	s_barrier
	global_load_lds_dwordx4 v[8:9], off
	v_lshl_add_u64 v[6:7], v[6:7], 0, s[64:65]
	s_add_i32 m0, s22, 0x1a000
	s_add_i32 s31, s22, 0x8000
	s_add_i32 s34, s22, 0xa000
	global_load_lds_dwordx4 v[6:7], off
	v_lshl_add_u64 v[4:5], v[4:5], 0, s[64:65]
	s_mov_b32 m0, s31
	s_add_u32 s36, s6, 0xb0080
	global_load_lds_dwordx4 v[4:5], off
	v_lshl_add_u64 v[2:3], v[2:3], 0, s[64:65]
	s_mov_b32 m0, s34
	s_addc_u32 s37, s7, 0
	global_load_lds_dwordx4 v[2:3], off
	s_add_i32 m0, s22, 0x1c000
	v_lshl_add_u64 v[2:3], s[36:37], 0, v[214:215]
	global_load_lds_dwordx4 v[2:3], off
	v_lshl_add_u64 v[2:3], s[36:37], 0, v[210:211]
	s_add_i32 m0, s22, 0x1e000
	v_readlane_b32 s35, v254, 57
	global_load_lds_dwordx4 v[2:3], off
	s_add_u32 s17, s35, s17
	s_addc_u32 s35, 0, 0
	s_add_u32 s17, s17, s14
	s_addc_u32 s35, s35, s15
	s_add_u32 s12, s12, s17
	s_addc_u32 s13, s13, s35
	s_add_u32 s35, s12, 0x9ab40100
	s_addc_u32 s36, s13, 0
	s_mul_i32 s16, s16, 0x160000
	s_add_u32 s14, s16, s14
	s_addc_u32 s15, 0, s15
	s_movk_i32 s16, 0xb00
	v_lshrrev_b32_e32 v3, 1, v10
	v_mul_lo_u32 v2, v11, s16
	s_mov_b32 s17, 0xb000
	s_add_u32 s37, s10, s14
	v_mad_u64_u32 v[2:3], s[12:13], v3, s17, v[2:3]
	s_addc_u32 s38, s11, s15
	v_or_b32_e32 v2, v2, v12
	s_add_u32 s10, s37, 0x263b0080
	v_add_lshl_u32 v2, v2, v15, 1
	v_mov_b32_e32 v3, v0
	s_addc_u32 s11, s38, 0
	v_lshl_add_u64 v[218:219], s[10:11], 0, v[2:3]
	v_lshrrev_b32_e32 v3, 1, v14
	v_mul_lo_u32 v2, v16, s16
	v_mad_u64_u32 v[2:3], s[12:13], v3, s17, v[2:3]
	v_or_b32_e32 v2, v2, v17
	s_waitcnt vmcnt(6)
	v_add_lshl_u32 v2, v2, v18, 1
	v_mov_b32_e32 v3, v0
	v_lshl_add_u64 v[220:221], s[10:11], 0, v[2:3]
	v_mov_b32_e32 v2, 0
	s_mov_b32 s39, -2
	s_mov_b64 s[10:11], 0
	v_add_u32_e32 v232, 0, v20
	v_mov_b32_e32 v3, v2
	v_mov_b64_e32 v[4:5], 0
	v_mov_b64_e32 v[6:7], 0
	v_mov_b64_e32 v[8:9], 0
	v_mov_b64_e32 v[10:11], 0
	v_mov_b64_e32 v[12:13], 0
	v_mov_b64_e32 v[14:15], 0
	v_mov_b64_e32 v[16:17], 0
	v_mov_b64_e32 v[22:23], 0
	v_mov_b64_e32 v[24:25], 0
	v_mov_b64_e32 v[30:31], 0
	v_mov_b64_e32 v[32:33], 0
	s_waitcnt vmcnt(0)
	v_mov_b64_e32 v[18:19], 0
	v_mov_b64_e32 v[20:21], 0
	v_mov_b64_e32 v[26:27], 0
	v_mov_b64_e32 v[28:29], 0
	v_mov_b64_e32 v[34:35], 0
	v_mov_b64_e32 v[36:37], 0
	v_mov_b64_e32 v[38:39], 0
	v_mov_b64_e32 v[40:41], 0
	v_mov_b64_e32 v[42:43], 0
	v_mov_b64_e32 v[44:45], 0
	v_mov_b64_e32 v[46:47], 0
	v_mov_b64_e32 v[48:49], 0
	v_mov_b64_e32 v[50:51], 0
	v_mov_b64_e32 v[52:53], 0
	v_mov_b64_e32 v[54:55], 0
	v_mov_b64_e32 v[56:57], 0
	v_mov_b64_e32 v[58:59], 0
	v_mov_b64_e32 v[60:61], 0
	v_mov_b64_e32 v[62:63], 0
	v_mov_b64_e32 v[64:65], 0
	v_mov_b64_e32 v[66:67], 0
	v_mov_b64_e32 v[68:69], 0
	v_mov_b64_e32 v[70:71], 0
	v_mov_b64_e32 v[72:73], 0
	v_mov_b64_e32 v[74:75], 0
	v_mov_b64_e32 v[76:77], 0
	v_mov_b64_e32 v[78:79], 0
	v_mov_b64_e32 v[80:81], 0
	v_mov_b64_e32 v[82:83], 0
	v_mov_b64_e32 v[84:85], 0
	v_mov_b64_e32 v[86:87], 0
	v_mov_b64_e32 v[88:89], 0
	v_mov_b64_e32 v[90:91], 0
	v_mov_b64_e32 v[92:93], 0
	v_mov_b64_e32 v[94:95], 0
	v_mov_b64_e32 v[96:97], 0
	v_mov_b64_e32 v[98:99], 0
	v_mov_b64_e32 v[100:101], 0
	v_mov_b64_e32 v[102:103], 0
	v_mov_b64_e32 v[104:105], 0
	v_mov_b64_e32 v[106:107], 0
	v_mov_b64_e32 v[108:109], 0
	v_mov_b64_e32 v[110:111], 0
	v_mov_b64_e32 v[112:113], 0
	v_mov_b64_e32 v[114:115], 0
	v_mov_b64_e32 v[116:117], 0
	v_mov_b64_e32 v[118:119], 0
	v_mov_b64_e32 v[120:121], 0
	v_mov_b64_e32 v[122:123], 0
	v_mov_b64_e32 v[124:125], 0
	v_mov_b64_e32 v[126:127], 0
	v_mov_b64_e32 v[128:129], 0
	s_barrier
	s_branch .LBB0_2111
